# v6 + GEMM1 epilogue: dead DPP zero-initialisers removed
# speedup vs baseline: 1.0051x; 1.0051x over previous
.LBB0_449:
	v_pk_mul_f32 v[112:113], v[112:113], v[186:187] op_sel_hi:[1,0]
	v_pk_mul_f32 v[114:115], v[114:115], v[186:187] op_sel_hi:[1,0]
	v_mul_f32_e32 v169, 0xbfb8aa3b, v112
	v_exp_f32_e32 v169, v169
	v_mul_f32_e32 v179, 0xbfb8aa3b, v114
	v_pk_mul_f32 v[126:127], v[126:127], v[186:187] op_sel_hi:[1,0]
	v_pk_mul_f32 v[124:125], v[124:125], v[186:187] op_sel_hi:[1,0]
	v_add_f32_e32 v169, 1.0, v169
	v_pk_mul_f32 v[122:123], v[122:123], v[186:187] op_sel_hi:[1,0]
	v_pk_mul_f32 v[120:121], v[120:121], v[186:187] op_sel_hi:[1,0]
	v_pk_mul_f32 v[118:119], v[118:119], v[186:187] op_sel_hi:[1,0]
	v_pk_mul_f32 v[116:117], v[116:117], v[186:187] op_sel_hi:[1,0]
	v_rcp_f32_e32 v196, v169
	v_mul_f32_e32 v169, 0xbfb8aa3b, v113
	v_exp_f32_e32 v179, v179
	v_mul_f32_e32 v186, 0xbfb8aa3b, v115
	v_exp_f32_e32 v169, v169
	v_exp_f32_e32 v186, v186
	v_add_f32_e32 v179, 1.0, v179
	v_rcp_f32_e32 v198, v179
	v_add_f32_e32 v169, 1.0, v169
	v_add_f32_e32 v179, 1.0, v186
	v_rcp_f32_e32 v199, v179
	v_rcp_f32_e32 v197, v169
	v_pk_mul_f32 v[118:119], v[122:123], v[118:119]
	v_pk_mul_f32 v[116:117], v[120:121], v[116:117]
	v_pk_mul_f32 v[114:115], v[114:115], v[198:199]
	v_pk_mul_f32 v[112:113], v[112:113], v[196:197]
	v_pk_mul_f32 v[114:115], v[126:127], v[114:115]
	v_pk_mul_f32 v[112:113], v[124:125], v[112:113]
	s_waitcnt lgkmcnt(0)
	v_cndmask_b32_e64 v138, v134, v138, s[6:7]
	v_cndmask_b32_e64 v139, v135, v139, s[6:7]
	v_mov_b32_dpp v125, v118 row_ror:2 row_mask:0xf bank_mask:0xf
	v_mov_b32_dpp v127, v119 row_ror:2 row_mask:0xf bank_mask:0xf
	v_cndmask_b32_e64 v136, v132, v136, s[6:7]
	v_cndmask_b32_e64 v137, v133, v137, s[6:7]
	v_mov_b32_dpp v121, v116 row_ror:2 row_mask:0xf bank_mask:0xf
	v_mov_b32_dpp v123, v117 row_ror:2 row_mask:0xf bank_mask:0xf
	v_mov_b32_dpp v124, v118 row_ror:1 row_mask:0xf bank_mask:0xf
	v_mov_b32_dpp v126, v119 row_ror:1 row_mask:0xf bank_mask:0xf
	v_cndmask_b32_e64 v138, v138, v125, s[8:9]
	v_cndmask_b32_e64 v139, v139, v127, s[8:9]
	v_mov_b32_dpp v120, v116 row_ror:1 row_mask:0xf bank_mask:0xf
	v_mov_b32_dpp v122, v117 row_ror:1 row_mask:0xf bank_mask:0xf
	v_cndmask_b32_e64 v136, v136, v121, s[8:9]
	v_cndmask_b32_e64 v137, v137, v123, s[8:9]
	v_cndmask_b32_e64 v134, v124, v134, s[6:7]
	v_cndmask_b32_e64 v135, v126, v135, s[6:7]
	v_pk_mul_f32 v[138:139], v[110:111], v[138:139]
	v_cndmask_b32_e64 v132, v120, v132, s[6:7]
	v_cndmask_b32_e64 v133, v122, v133, s[6:7]
	v_pk_mul_f32 v[136:137], v[108:109], v[136:137]
	v_pk_fma_f32 v[134:135], v[106:107], v[134:135], v[138:139]
	v_pk_fma_f32 v[132:133], v[104:105], v[132:133], v[136:137]
	v_pk_fma_f32 v[118:119], v[118:119], v[102:103], v[134:135]
	v_lshlrev_b64 v[134:135], 11, v[184:185]
	v_pk_fma_f32 v[116:117], v[116:117], v[100:101], v[132:133]
	v_lshl_add_u64 v[134:135], s[18:19], 0, v[134:135]
	v_pk_mul_f32 v[118:119], v[114:115], v[118:119]
	v_pk_mul_f32 v[116:117], v[112:113], v[116:117]
	v_lshl_add_u64 v[134:135], v[172:173], 1, v[134:135]
	v_cvt_pk_bf16_f32 v132, v116, v117
	v_cvt_pk_bf16_f32 v133, v118, v119
	global_store_dwordx2 v[134:135], v[132:133], off
	s_and_saveexec_b64 s[62:63], s[46:47]
	s_cbranch_execz .LBB0_451
	s_ashr_i32 s53, s52, 31
	s_lshl_b64 s[64:65], s[52:53], 13
	v_lshl_add_u64 v[132:133], v[146:147], 0, s[64:65]
	v_lshl_add_u64 v[132:133], v[132:133], 0, v[174:175]
	global_store_dwordx4 v[132:133], v[112:115], off
	v_lshl_add_u64 v[132:133], v[148:149], 0, s[64:65]
	v_lshl_add_u64 v[132:133], v[132:133], 0, v[174:175]
	global_store_dwordx4 v[132:133], v[116:119], off
.LBB0_451:
	s_or_b64 exec, exec, s[62:63]
	v_pk_mul_f32 v[88:89], v[88:89], v[182:183] op_sel_hi:[1,0]
	v_pk_mul_f32 v[84:85], v[84:85], v[182:183] op_sel_hi:[1,0]
	v_pk_mul_f32 v[64:65], v[64:65], v[180:181] op_sel_hi:[1,0]
	v_pk_mul_f32 v[84:85], v[88:89], v[84:85]
	v_mul_f32_e32 v88, 0xbfb8aa3b, v64
	v_mul_f32_e32 v89, 0xbfb8aa3b, v65
	v_exp_f32_e32 v88, v88
	v_exp_f32_e32 v89, v89
	v_mov_b32_e32 v179, v178
	v_pk_mul_f32 v[76:77], v[76:77], v[180:181] op_sel_hi:[1,0]
	v_add_f32_e32 v88, 1.0, v88
	v_add_f32_e32 v89, 1.0, v89
	v_rcp_f32_e32 v88, v88
	v_rcp_f32_e32 v89, v89
	v_pk_mul_f32 v[72:73], v[72:73], v[180:181] op_sel_hi:[1,0]
	v_pk_mul_f32 v[68:69], v[68:69], v[180:181] op_sel_hi:[1,0]
	v_pk_mul_f32 v[56:57], v[56:57], v[178:179]
	v_pk_mul_f32 v[64:65], v[64:65], v[88:89]
	v_pk_mul_f32 v[74:75], v[74:75], v[180:181] op_sel_hi:[1,0]
	v_pk_mul_f32 v[70:71], v[70:71], v[180:181] op_sel_hi:[1,0]
	v_pk_mul_f32 v[68:69], v[72:73], v[68:69]
	v_pk_mul_f32 v[72:73], v[76:77], v[64:65]
	v_mul_f32_e32 v64, 0xbfb8aa3b, v56
	v_pk_mul_f32 v[90:91], v[90:91], v[182:183] op_sel_hi:[1,0]
	v_pk_mul_f32 v[86:87], v[86:87], v[182:183] op_sel_hi:[1,0]
	v_pk_mul_f32 v[66:67], v[66:67], v[180:181] op_sel_hi:[1,0]
	v_pk_mul_f32 v[70:71], v[74:75], v[70:71]
	v_exp_f32_e32 v74, v64
	v_mov_b32_e32 v64, v178
	v_mov_b32_e32 v65, v178
	v_pk_mul_f32 v[86:87], v[90:91], v[86:87]
	v_mul_f32_e32 v90, 0xbfb8aa3b, v66
	v_mul_f32_e32 v91, 0xbfb8aa3b, v67
	v_pk_mul_f32 v[58:59], v[58:59], v[64:65]
	v_exp_f32_e32 v90, v90
	v_exp_f32_e32 v91, v91
	v_mul_f32_e32 v76, 0xbfb8aa3b, v58
	v_mul_f32_e32 v77, 0xbfb8aa3b, v59
	v_exp_f32_e32 v76, v76
	v_exp_f32_e32 v77, v77
	v_mul_f32_e32 v75, 0xbfb8aa3b, v57
	v_pk_mul_f32 v[80:81], v[80:81], v[182:183] op_sel_hi:[1,0]
	v_pk_mul_f32 v[82:83], v[82:83], v[182:183] op_sel_hi:[1,0]
	v_exp_f32_e32 v75, v75
	v_mul_f32_e32 v116, 0xbfb8aa3b, v80
	v_mul_f32_e32 v117, 0xbfb8aa3b, v81
	v_mul_f32_e32 v118, 0xbfb8aa3b, v82
	v_mul_f32_e32 v119, 0xbfb8aa3b, v83
	v_add_f32_e32 v90, 1.0, v90
	v_add_f32_e32 v91, 1.0, v91
	v_exp_f32_e32 v116, v116
	v_exp_f32_e32 v117, v117
	v_exp_f32_e32 v118, v118
	v_exp_f32_e32 v119, v119
	v_rcp_f32_e32 v90, v90
	v_rcp_f32_e32 v91, v91
	v_add_f32_e32 v76, 1.0, v76
	v_add_f32_e32 v77, 1.0, v77
	v_rcp_f32_e32 v76, v76
	v_rcp_f32_e32 v77, v77
	v_add_f32_e32 v74, 1.0, v74
	v_add_f32_e32 v75, 1.0, v75
	v_rcp_f32_e32 v74, v74
	v_rcp_f32_e32 v75, v75
	v_add_f32_e32 v116, 1.0, v116
	v_add_f32_e32 v117, 1.0, v117
	v_add_f32_e32 v118, 1.0, v118
	v_add_f32_e32 v119, 1.0, v119
	v_pk_mul_f32 v[78:79], v[78:79], v[180:181] op_sel_hi:[1,0]
	v_pk_mul_f32 v[66:67], v[66:67], v[90:91]
	v_rcp_f32_e32 v116, v116
	v_rcp_f32_e32 v118, v118
	v_rcp_f32_e32 v119, v119
	v_rcp_f32_e32 v117, v117
	v_pk_mul_f32 v[66:67], v[78:79], v[66:67]
	v_pk_mul_f32 v[58:59], v[58:59], v[76:77]
	v_pk_mul_f32 v[62:63], v[62:63], v[64:65]
	v_mov_b32_dpp v77, v84 row_ror:2 row_mask:0xf bank_mask:0xf
	v_mov_b32_dpp v79, v85 row_ror:2 row_mask:0xf bank_mask:0xf
	v_mov_b32_dpp v89, v86 row_ror:2 row_mask:0xf bank_mask:0xf
	v_mov_b32_dpp v91, v87 row_ror:2 row_mask:0xf bank_mask:0xf
	v_pk_mul_f32 v[60:61], v[60:61], v[178:179]
	v_pk_mul_f32 v[56:57], v[56:57], v[74:75]
	v_pk_mul_f32 v[58:59], v[62:63], v[58:59]
	v_mov_b32_dpp v76, v84 row_ror:1 row_mask:0xf bank_mask:0xf
	v_mov_b32_dpp v78, v85 row_ror:1 row_mask:0xf bank_mask:0xf
	v_mov_b32_dpp v88, v86 row_ror:1 row_mask:0xf bank_mask:0xf
	v_mov_b32_dpp v90, v87 row_ror:1 row_mask:0xf bank_mask:0xf
	v_cndmask_b32_e64 v62, v121, v77, s[8:9]
	v_cndmask_b32_e64 v63, v123, v79, s[8:9]
	v_cndmask_b32_e64 v74, v125, v89, s[8:9]
	v_cndmask_b32_e64 v75, v127, v91, s[8:9]
	v_pk_mul_f32 v[56:57], v[60:61], v[56:57]
	v_cndmask_b32_e64 v60, v76, v120, s[6:7]
	v_cndmask_b32_e64 v61, v78, v122, s[6:7]
	v_cndmask_b32_e64 v64, v88, v124, s[6:7]
	v_cndmask_b32_e64 v65, v90, v126, s[6:7]
	v_pk_mul_f32 v[74:75], v[110:111], v[74:75]
	v_pk_mul_f32 v[62:63], v[108:109], v[62:63]
	v_pk_mul_f32 v[98:99], v[98:99], v[182:183] op_sel_hi:[1,0]
	v_pk_mul_f32 v[96:97], v[96:97], v[182:183] op_sel_hi:[1,0]
	v_pk_mul_f32 v[82:83], v[82:83], v[118:119]
	v_pk_mul_f32 v[80:81], v[80:81], v[116:117]
	v_pk_fma_f32 v[64:65], v[106:107], v[64:65], v[74:75]
	v_pk_fma_f32 v[60:61], v[104:105], v[60:61], v[62:63]
	v_pk_mul_f32 v[82:83], v[98:99], v[82:83]
	v_pk_mul_f32 v[80:81], v[96:97], v[80:81]
	v_pk_fma_f32 v[62:63], v[86:87], v[102:103], v[64:65]
	v_pk_fma_f32 v[60:61], v[84:85], v[100:101], v[60:61]
	v_add_u32_e32 v64, s55, v181
	v_pk_mul_f32 v[62:63], v[82:83], v[62:63]
	v_pk_mul_f32 v[60:61], v[80:81], v[60:61]
	v_ashrrev_i32_e32 v65, 31, v64
	v_cvt_pk_bf16_f32 v60, v60, v61
	v_cvt_pk_bf16_f32 v61, v62, v63
	v_lshlrev_b64 v[62:63], 11, v[64:65]
	v_lshl_add_u64 v[62:63], s[18:19], 0, v[62:63]
	v_lshlrev_b64 v[64:65], 1, v[172:173]
	v_lshl_add_u64 v[62:63], v[62:63], 0, v[64:65]
	v_mov_b32_dpp v80, v68 row_ror:1 row_mask:0xf bank_mask:0xf
	v_mov_b32_dpp v81, v68 row_ror:2 row_mask:0xf bank_mask:0xf
	v_mov_b32_dpp v85, v70 row_ror:2 row_mask:0xf bank_mask:0xf
	v_mov_b32_dpp v87, v71 row_ror:2 row_mask:0xf bank_mask:0xf
	global_store_dwordx2 v[62:63], v[60:61], off
	v_mov_b32_dpp v83, v69 row_ror:2 row_mask:0xf bank_mask:0xf
	v_mov_b32_dpp v84, v70 row_ror:1 row_mask:0xf bank_mask:0xf
	v_mov_b32_dpp v86, v71 row_ror:1 row_mask:0xf bank_mask:0xf
	v_cndmask_b32_e64 v60, v80, v76, s[6:7]
	v_cndmask_b32_e64 v62, v77, v81, s[8:9]
	v_cndmask_b32_e64 v76, v89, v85, s[8:9]
	v_cndmask_b32_e64 v77, v91, v87, s[8:9]
	v_mov_b32_dpp v82, v69 row_ror:1 row_mask:0xf bank_mask:0xf
	v_cndmask_b32_e64 v63, v79, v83, s[8:9]
	v_cndmask_b32_e64 v74, v84, v88, s[6:7]
	v_cndmask_b32_e64 v75, v86, v90, s[6:7]
	v_pk_mul_f32 v[76:77], v[110:111], v[76:77]
	v_cndmask_b32_e64 v61, v82, v78, s[6:7]
	v_pk_mul_f32 v[62:63], v[108:109], v[62:63]
	v_pk_fma_f32 v[74:75], v[106:107], v[74:75], v[76:77]
	v_pk_fma_f32 v[60:61], v[104:105], v[60:61], v[62:63]
	v_pk_fma_f32 v[62:63], v[70:71], v[102:103], v[74:75]
	v_pk_fma_f32 v[60:61], v[68:69], v[100:101], v[60:61]
	v_pk_mul_f32 v[62:63], v[66:67], v[62:63]
	v_add_u32_e32 v66, s55, v183
	v_pk_mul_f32 v[60:61], v[72:73], v[60:61]
	v_ashrrev_i32_e32 v67, 31, v66
	v_cvt_pk_bf16_f32 v60, v60, v61
	v_cvt_pk_bf16_f32 v61, v62, v63
	v_lshlrev_b64 v[62:63], 11, v[66:67]
	v_lshl_add_u64 v[62:63], s[18:19], 0, v[62:63]
	v_lshl_add_u64 v[62:63], v[62:63], 0, v[64:65]
	global_store_dwordx2 v[62:63], v[60:61], off
	v_mov_b32_dpp v61, v128 row_ror:2 row_mask:0xf bank_mask:0xf
	v_mov_b32_dpp v63, v129 row_ror:1 row_mask:0xf bank_mask:0xf
	v_mov_b32_dpp v66, v129 row_ror:2 row_mask:0xf bank_mask:0xf
	v_mov_b32_dpp v60, v128 row_ror:1 row_mask:0xf bank_mask:0xf
	v_mov_b32_dpp v67, v130 row_ror:1 row_mask:0xf bank_mask:0xf
	v_mov_b32_dpp v68, v130 row_ror:2 row_mask:0xf bank_mask:0xf
	v_mov_b32_dpp v69, v131 row_ror:1 row_mask:0xf bank_mask:0xf
	v_mov_b32_dpp v70, v131 row_ror:2 row_mask:0xf bank_mask:0xf
	v_cndmask_b32_e64 v62, v81, v61, s[8:9]
	v_cndmask_b32_e64 v61, v63, v82, s[6:7]
	v_cndmask_b32_e64 v63, v83, v66, s[8:9]
	v_cndmask_b32_e64 v60, v60, v80, s[6:7]
	v_cndmask_b32_e64 v66, v67, v84, s[6:7]
	v_cndmask_b32_e64 v68, v85, v68, s[8:9]
	v_cndmask_b32_e64 v67, v69, v86, s[6:7]
	v_cndmask_b32_e64 v69, v87, v70, s[8:9]
	v_pk_mul_f32 v[62:63], v[108:109], v[62:63]
	v_pk_mul_f32 v[68:69], v[110:111], v[68:69]
	v_pk_fma_f32 v[60:61], v[104:105], v[60:61], v[62:63]
	v_pk_fma_f32 v[66:67], v[106:107], v[66:67], v[68:69]
	v_pk_fma_f32 v[60:61], v[128:129], v[100:101], v[60:61]
	v_pk_fma_f32 v[62:63], v[130:131], v[102:103], v[66:67]
	v_pk_mul_f32 v[56:57], v[56:57], v[60:61]
	v_add_u32_e32 v60, s55, v187
	v_pk_mul_f32 v[58:59], v[58:59], v[62:63]
	v_ashrrev_i32_e32 v61, 31, v60
	v_cvt_pk_bf16_f32 v56, v56, v57
	v_cvt_pk_bf16_f32 v57, v58, v59
	v_lshlrev_b64 v[58:59], 11, v[60:61]
	v_lshl_add_u64 v[58:59], s[18:19], 0, v[58:59]
	v_lshl_add_u64 v[58:59], v[58:59], 0, v[64:65]
	global_store_dwordx2 v[58:59], v[56:57], off
	v_mov_b32_e32 v60, 0
	s_andn2_b64 vcc, exec, s[48:49]
	v_mov_b32_e32 v61, 0
	v_mov_b32_e32 v62, 0
	v_mov_b32_e32 v63, 0
	v_mov_b32_e32 v56, 0
	v_mov_b32_e32 v57, 0
	v_mov_b32_e32 v58, 0
	v_mov_b32_e32 v59, 0
	s_cbranch_vccnz .LBB0_453
	ds_read_b128 v[60:63], v191
	ds_read_b128 v[56:59], v190
.LBB0_453:
	v_pk_mul_f32 v[40:41], v[40:41], v[176:177] op_sel_hi:[1,0]
	v_pk_mul_f32 v[42:43], v[42:43], v[176:177] op_sel_hi:[1,0]
	v_mul_f32_e32 v66, 0xbfb8aa3b, v40
	v_mul_f32_e32 v67, 0xbfb8aa3b, v41
	v_mul_f32_e32 v68, 0xbfb8aa3b, v42
	v_mul_f32_e32 v69, 0xbfb8aa3b, v43
	v_exp_f32_e32 v66, v66
	v_exp_f32_e32 v67, v67
	v_exp_f32_e32 v68, v68
	v_exp_f32_e32 v69, v69
	v_add_f32_e32 v66, 1.0, v66
	v_add_f32_e32 v67, 1.0, v67
	v_add_f32_e32 v68, 1.0, v68
	v_add_f32_e32 v69, 1.0, v69
	v_rcp_f32_e32 v66, v66
	v_rcp_f32_e32 v68, v68
	v_rcp_f32_e32 v69, v69
	v_rcp_f32_e32 v67, v67
	v_pk_mul_f32 v[50:51], v[50:51], v[176:177] op_sel_hi:[1,0]
	v_pk_mul_f32 v[48:49], v[48:49], v[176:177] op_sel_hi:[1,0]
	v_pk_mul_f32 v[46:47], v[46:47], v[176:177] op_sel_hi:[1,0]
	v_pk_mul_f32 v[44:45], v[44:45], v[176:177] op_sel_hi:[1,0]
	v_pk_mul_f32 v[54:55], v[54:55], v[176:177] op_sel_hi:[1,0]
	v_pk_mul_f32 v[52:53], v[52:53], v[176:177] op_sel_hi:[1,0]
	v_pk_mul_f32 v[70:71], v[50:51], v[46:47]
	v_pk_mul_f32 v[72:73], v[48:49], v[44:45]
	v_pk_mul_f32 v[42:43], v[42:43], v[68:69]
	v_pk_mul_f32 v[40:41], v[40:41], v[66:67]
	v_pk_mul_f32 v[42:43], v[54:55], v[42:43]
	v_pk_mul_f32 v[40:41], v[52:53], v[40:41]
	s_waitcnt lgkmcnt(0)
	v_cndmask_b32_e64 v53, v56, v60, s[6:7]
	v_cndmask_b32_e64 v55, v57, v61, s[6:7]
	v_cndmask_b32_e64 v60, v58, v62, s[6:7]
	v_cndmask_b32_e64 v61, v59, v63, s[6:7]
	v_mov_b32_dpp v44, v72 row_ror:1 row_mask:0xf bank_mask:0xf
	v_mov_b32_dpp v45, v72 row_ror:2 row_mask:0xf bank_mask:0xf
	v_mov_b32_dpp v46, v73 row_ror:1 row_mask:0xf bank_mask:0xf
	v_mov_b32_dpp v48, v70 row_ror:1 row_mask:0xf bank_mask:0xf
	v_mov_b32_dpp v49, v70 row_ror:2 row_mask:0xf bank_mask:0xf
	v_mov_b32_dpp v50, v71 row_ror:1 row_mask:0xf bank_mask:0xf
	v_mov_b32_dpp v51, v71 row_ror:2 row_mask:0xf bank_mask:0xf
	v_mov_b32_dpp v47, v73 row_ror:2 row_mask:0xf bank_mask:0xf
	v_cndmask_b32_e64 v52, v44, v56, s[6:7]
	v_cndmask_b32_e64 v54, v53, v45, s[8:9]
	v_cndmask_b32_e64 v53, v46, v57, s[6:7]
	v_cndmask_b32_e64 v56, v48, v58, s[6:7]
	v_cndmask_b32_e64 v58, v60, v49, s[8:9]
	v_cndmask_b32_e64 v57, v50, v59, s[6:7]
	v_cndmask_b32_e64 v59, v61, v51, s[8:9]
	v_cndmask_b32_e64 v55, v55, v47, s[8:9]
	v_pk_mul_f32 v[58:59], v[110:111], v[58:59]
	v_pk_mul_f32 v[54:55], v[108:109], v[54:55]
	v_pk_fma_f32 v[56:57], v[106:107], v[56:57], v[58:59]
	v_pk_fma_f32 v[52:53], v[104:105], v[52:53], v[54:55]
	v_pk_fma_f32 v[54:55], v[70:71], v[102:103], v[56:57]
	v_pk_fma_f32 v[52:53], v[72:73], v[100:101], v[52:53]
	v_pk_mul_f32 v[42:43], v[42:43], v[54:55]
	v_lshlrev_b64 v[54:55], 11, v[170:171]
	v_lshl_add_u64 v[54:55], s[18:19], 0, v[54:55]
	v_pk_mul_f32 v[40:41], v[40:41], v[52:53]
	v_lshl_add_u64 v[54:55], v[172:173], 1, v[54:55]
	v_cvt_pk_bf16_f32 v52, v40, v41
	v_cvt_pk_bf16_f32 v53, v42, v43
	global_store_dwordx2 v[54:55], v[52:53], off
	s_and_saveexec_b64 s[62:63], s[50:51]
	s_cbranch_execz .LBB0_455
	s_ashr_i32 s53, s52, 31
	s_lshl_b64 s[52:53], s[52:53], 13
	v_lshl_add_u64 v[52:53], v[146:147], 0, s[52:53]
	v_lshl_add_u64 v[52:53], v[52:53], 0, v[174:175]
	global_store_dwordx4 v[52:53], v[112:115], off
	v_lshl_add_u64 v[52:53], v[148:149], 0, s[52:53]
	v_lshl_add_u64 v[52:53], v[52:53], 0, v[174:175]
	global_store_dwordx4 v[52:53], v[40:43], off
.LBB0_455:
	s_or_b64 exec, exec, s[62:63]
	v_mov_b32_e32 v169, v168
	v_pk_mul_f32 v[32:33], v[32:33], v[168:169]
	v_mov_b32_e32 v41, v168
	v_mul_f32_e32 v40, 0xbfb8aa3b, v32
	v_mul_f32_e32 v43, 0xbfb8aa3b, v33
	v_exp_f32_e32 v42, v40
	v_exp_f32_e32 v43, v43
	v_mov_b32_e32 v40, v168
	v_pk_mul_f32 v[34:35], v[34:35], v[40:41]
	v_add_f32_e32 v42, 1.0, v42
	v_add_f32_e32 v43, 1.0, v43
	v_rcp_f32_e32 v42, v42
	v_rcp_f32_e32 v43, v43
	v_mul_f32_e32 v52, 0xbfb8aa3b, v34
	v_mul_f32_e32 v53, 0xbfb8aa3b, v35
	v_pk_mul_f32 v[36:37], v[36:37], v[168:169]
	v_pk_mul_f32 v[32:33], v[32:33], v[42:43]
	v_pk_mul_f32 v[20:21], v[20:21], v[166:167] op_sel_hi:[1,0]
	v_exp_f32_e32 v52, v52
	v_exp_f32_e32 v53, v53
	v_pk_mul_f32 v[38:39], v[38:39], v[40:41]
	v_mul_f32_e32 v40, 0xbfb8aa3b, v20
	v_pk_mul_f32 v[32:33], v[36:37], v[32:33]
	v_mul_f32_e32 v37, 0xbfb8aa3b, v21
	v_exp_f32_e32 v40, v40
	v_exp_f32_e32 v37, v37
	v_add_f32_e32 v52, 1.0, v52
	v_add_f32_e32 v53, 1.0, v53
	v_rcp_f32_e32 v52, v52
	v_rcp_f32_e32 v53, v53
	v_add_f32_e32 v36, 1.0, v40
	v_add_f32_e32 v37, 1.0, v37
	v_rcp_f32_e32 v36, v36
	v_rcp_f32_e32 v37, v37
	v_pk_mul_f32 v[34:35], v[34:35], v[52:53]
	v_pk_mul_f32 v[22:23], v[22:23], v[166:167] op_sel_hi:[1,0]
	v_pk_mul_f32 v[34:35], v[38:39], v[34:35]
	v_mul_f32_e32 v38, 0xbfb8aa3b, v22
	v_mul_f32_e32 v39, 0xbfb8aa3b, v23
	v_pk_mul_f32 v[28:29], v[28:29], v[166:167] op_sel_hi:[1,0]
	v_pk_mul_f32 v[20:21], v[20:21], v[36:37]
	v_pk_mul_f32 v[26:27], v[26:27], v[166:167] op_sel_hi:[1,0]
	v_pk_mul_f32 v[24:25], v[24:25], v[166:167] op_sel_hi:[1,0]
	v_pk_mul_f32 v[14:15], v[14:15], v[166:167] op_sel_hi:[1,0]
	v_pk_mul_f32 v[12:13], v[12:13], v[166:167] op_sel_hi:[1,0]
	v_pk_mul_f32 v[4:5], v[4:5], v[164:165] op_sel_hi:[1,0]
	v_pk_mul_f32 v[6:7], v[6:7], v[164:165] op_sel_hi:[1,0]
	v_exp_f32_e32 v38, v38
	v_exp_f32_e32 v39, v39
	v_pk_mul_f32 v[20:21], v[28:29], v[20:21]
	v_mul_f32_e32 v28, 0xbfb8aa3b, v4
	v_pk_mul_f32 v[14:15], v[26:27], v[14:15]
	v_pk_mul_f32 v[12:13], v[24:25], v[12:13]
	v_mul_f32_e32 v25, 0xbfb8aa3b, v5
	v_mul_f32_e32 v26, 0xbfb8aa3b, v6
	v_mul_f32_e32 v27, 0xbfb8aa3b, v7
	v_exp_f32_e32 v28, v28
	v_exp_f32_e32 v25, v25
	v_exp_f32_e32 v26, v26
	v_exp_f32_e32 v27, v27
	v_add_f32_e32 v38, 1.0, v38
	v_add_f32_e32 v39, 1.0, v39
	v_rcp_f32_e32 v38, v38
	v_rcp_f32_e32 v39, v39
	v_add_f32_e32 v24, 1.0, v28
	v_add_f32_e32 v25, 1.0, v25
	v_add_f32_e32 v26, 1.0, v26
	v_add_f32_e32 v27, 1.0, v27
	v_rcp_f32_e32 v24, v24
	v_rcp_f32_e32 v26, v26
	v_rcp_f32_e32 v27, v27
	v_rcp_f32_e32 v25, v25
	v_pk_mul_f32 v[30:31], v[30:31], v[166:167] op_sel_hi:[1,0]
	v_pk_mul_f32 v[22:23], v[22:23], v[38:39]
	v_pk_mul_f32 v[10:11], v[10:11], v[164:165] op_sel_hi:[1,0]
	v_pk_mul_f32 v[8:9], v[8:9], v[164:165] op_sel_hi:[1,0]
	v_pk_mul_f32 v[2:3], v[2:3], v[164:165] op_sel_hi:[1,0]
	v_pk_mul_f32 v[0:1], v[0:1], v[164:165] op_sel_hi:[1,0]
	v_pk_mul_f32 v[22:23], v[30:31], v[22:23]
	v_pk_mul_f32 v[6:7], v[6:7], v[26:27]
	v_pk_mul_f32 v[4:5], v[4:5], v[24:25]
	v_pk_mul_f32 v[2:3], v[10:11], v[2:3]
	v_pk_mul_f32 v[0:1], v[8:9], v[0:1]
	v_pk_mul_f32 v[18:19], v[18:19], v[164:165] op_sel_hi:[1,0]
	s_nop 0
	v_mov_b32_dpp v25, v0 row_ror:2 row_mask:0xf bank_mask:0xf
	v_mov_b32_dpp v27, v1 row_ror:2 row_mask:0xf bank_mask:0xf
	v_mov_b32_dpp v29, v2 row_ror:2 row_mask:0xf bank_mask:0xf
	v_mov_b32_dpp v31, v3 row_ror:2 row_mask:0xf bank_mask:0xf
	v_pk_mul_f32 v[16:17], v[16:17], v[164:165] op_sel_hi:[1,0]
	v_pk_mul_f32 v[6:7], v[18:19], v[6:7]
	v_mov_b32_dpp v24, v0 row_ror:1 row_mask:0xf bank_mask:0xf
	v_mov_b32_dpp v26, v1 row_ror:1 row_mask:0xf bank_mask:0xf
	v_mov_b32_dpp v28, v2 row_ror:1 row_mask:0xf bank_mask:0xf
	v_mov_b32_dpp v30, v3 row_ror:1 row_mask:0xf bank_mask:0xf
	v_cndmask_b32_e64 v10, v45, v25, s[8:9]
	v_cndmask_b32_e64 v11, v47, v27, s[8:9]
	v_cndmask_b32_e64 v18, v49, v29, s[8:9]
	v_cndmask_b32_e64 v19, v51, v31, s[8:9]
	v_pk_mul_f32 v[4:5], v[16:17], v[4:5]
	v_cndmask_b32_e64 v8, v24, v44, s[6:7]
	v_cndmask_b32_e64 v9, v26, v46, s[6:7]
	v_cndmask_b32_e64 v16, v28, v48, s[6:7]
	v_cndmask_b32_e64 v17, v30, v50, s[6:7]
	v_pk_mul_f32 v[18:19], v[110:111], v[18:19]
	v_pk_mul_f32 v[10:11], v[108:109], v[10:11]
	v_pk_fma_f32 v[16:17], v[106:107], v[16:17], v[18:19]
	v_pk_fma_f32 v[8:9], v[104:105], v[8:9], v[10:11]
	v_pk_fma_f32 v[2:3], v[2:3], v[102:103], v[16:17]
	v_pk_fma_f32 v[0:1], v[0:1], v[100:101], v[8:9]
	v_pk_mul_f32 v[2:3], v[6:7], v[2:3]
	v_pk_mul_f32 v[0:1], v[4:5], v[0:1]
	v_cvt_pk_bf16_f32 v0, v0, v1
	v_cvt_pk_bf16_f32 v1, v2, v3
	v_lshlrev_b64 v[2:3], 11, v[162:163]
	v_lshl_add_u64 v[2:3], s[18:19], 0, v[2:3]
	v_lshl_add_u64 v[2:3], v[2:3], 0, v[64:65]
	v_mov_b32_dpp v9, v12 row_ror:2 row_mask:0xf bank_mask:0xf
	v_mov_b32_dpp v11, v13 row_ror:2 row_mask:0xf bank_mask:0xf
	v_mov_b32_dpp v17, v14 row_ror:2 row_mask:0xf bank_mask:0xf
	v_mov_b32_dpp v19, v15 row_ror:2 row_mask:0xf bank_mask:0xf
	global_store_dwordx2 v[2:3], v[0:1], off
	v_mov_b32_dpp v8, v12 row_ror:1 row_mask:0xf bank_mask:0xf
	v_mov_b32_dpp v10, v13 row_ror:1 row_mask:0xf bank_mask:0xf
	v_mov_b32_dpp v16, v14 row_ror:1 row_mask:0xf bank_mask:0xf
	v_mov_b32_dpp v18, v15 row_ror:1 row_mask:0xf bank_mask:0xf
	v_cndmask_b32_e64 v2, v25, v9, s[8:9]
	v_cndmask_b32_e64 v3, v27, v11, s[8:9]
	v_cndmask_b32_e64 v6, v29, v17, s[8:9]
	v_cndmask_b32_e64 v7, v31, v19, s[8:9]
	v_cndmask_b32_e64 v0, v8, v24, s[6:7]
	v_cndmask_b32_e64 v1, v10, v26, s[6:7]
	v_cndmask_b32_e64 v4, v16, v28, s[6:7]
	v_cndmask_b32_e64 v5, v18, v30, s[6:7]
	v_pk_mul_f32 v[6:7], v[110:111], v[6:7]
	v_pk_mul_f32 v[2:3], v[108:109], v[2:3]
	v_pk_fma_f32 v[4:5], v[106:107], v[4:5], v[6:7]
	v_pk_fma_f32 v[0:1], v[104:105], v[0:1], v[2:3]
	v_pk_fma_f32 v[2:3], v[14:15], v[102:103], v[4:5]
	v_pk_fma_f32 v[0:1], v[12:13], v[100:101], v[0:1]
	v_pk_mul_f32 v[2:3], v[22:23], v[2:3]
	v_pk_mul_f32 v[0:1], v[20:21], v[0:1]
	v_cvt_pk_bf16_f32 v0, v0, v1
	v_cvt_pk_bf16_f32 v1, v2, v3
	v_lshlrev_b64 v[2:3], 11, v[160:161]
	v_lshl_add_u64 v[2:3], s[18:19], 0, v[2:3]
	v_lshl_add_u64 v[2:3], v[2:3], 0, v[64:65]
	global_store_dwordx2 v[2:3], v[0:1], off
	v_mov_b32_dpp v1, v92 row_ror:2 row_mask:0xf bank_mask:0xf
	v_mov_b32_dpp v3, v93 row_ror:1 row_mask:0xf bank_mask:0xf
	v_mov_b32_dpp v4, v93 row_ror:2 row_mask:0xf bank_mask:0xf
	v_mov_b32_dpp v5, v94 row_ror:1 row_mask:0xf bank_mask:0xf
	v_mov_b32_dpp v6, v94 row_ror:2 row_mask:0xf bank_mask:0xf
	v_mov_b32_dpp v7, v95 row_ror:1 row_mask:0xf bank_mask:0xf
	v_mov_b32_dpp v12, v95 row_ror:2 row_mask:0xf bank_mask:0xf
	v_mov_b32_dpp v0, v92 row_ror:1 row_mask:0xf bank_mask:0xf
	v_cndmask_b32_e64 v2, v9, v1, s[8:9]
	v_cndmask_b32_e64 v1, v3, v10, s[6:7]
	v_cndmask_b32_e64 v3, v11, v4, s[8:9]
	v_cndmask_b32_e64 v4, v5, v16, s[6:7]
	v_cndmask_b32_e64 v6, v17, v6, s[8:9]
	v_cndmask_b32_e64 v5, v7, v18, s[6:7]
	v_cndmask_b32_e64 v7, v19, v12, s[8:9]
	v_cndmask_b32_e64 v0, v0, v8, s[6:7]
	v_pk_mul_f32 v[6:7], v[110:111], v[6:7]
	v_pk_mul_f32 v[2:3], v[108:109], v[2:3]
	v_pk_fma_f32 v[4:5], v[106:107], v[4:5], v[6:7]
	v_pk_fma_f32 v[0:1], v[104:105], v[0:1], v[2:3]
	v_pk_fma_f32 v[2:3], v[94:95], v[102:103], v[4:5]
	v_pk_fma_f32 v[0:1], v[92:93], v[100:101], v[0:1]
	v_pk_mul_f32 v[2:3], v[34:35], v[2:3]
	v_pk_mul_f32 v[0:1], v[32:33], v[0:1]
	s_andn2_b64 vcc, exec, s[10:11]
	v_cvt_pk_bf16_f32 v0, v0, v1
	v_cvt_pk_bf16_f32 v1, v2, v3
	v_lshlrev_b64 v[2:3], 11, v[158:159]
	v_lshl_add_u64 v[2:3], s[18:19], 0, v[2:3]
	v_lshl_add_u64 v[2:3], v[2:3], 0, v[64:65]
	global_store_dwordx2 v[2:3], v[0:1], off
	s_waitcnt lgkmcnt(0)
	s_mov_b64 s[10:11], -1
	s_cbranch_vccnz .LBB0_431
	s_andn2_b64 vcc, exec, s[16:17]
	s_cbranch_vccnz .LBB0_430
	s_barrier
	s_branch .LBB0_430
